# pool-weight fold staging: all 16 per-thread w_in loads issued together before the LDS writes (was 2/4 loads per iteration, each waited), both layer copies; on top of v21
# speedup vs baseline: 1.0284x; 1.0284x over previous
; __device__ __forceinline__ void phase_convert(PP p, int l, LAS unsigned char* lds, int tid, int lane, int wave) {
;     ...
;         for (int item = blockIdx.x; item < 256; item += gridDim.x) {
;             const int kb = item >> 2, g = item & 3, k0 = kb * 32;
;             for (int i = tid; i < 32 * 256; i += 512) { const int r = i >> 8, cc = i & 255; AtT[cc * 36 + r] = w_in[(size_t)(k0 + r) * INP + g * 256 + cc]; }
;             __syncthreads();
.LBB0_27:
	s_lshl_b32 s10, s39, 3
	s_and_b32 s25, s39, 3
	s_and_b32 s24, s10, 0xffffffe0
	s_and_saveexec_b64 s[26:27], vcc
	s_cbranch_execz .LBB0_39
	s_lshl_b32 s22, s25, 10
	v_lshl_add_u64 v[10:11], v[6:7], 0, s[22:23]
	v_ashrrev_i32_e32 v12, 8, v2
	v_add_u32_e32 v14, s24, v12
	v_mad_i64_i32 v[14:15], s[10:11], v14, s1, v[10:11]
	v_lshl_add_u32 v12, v12, 2, v28
	s_lshl_b32 s98, s1, 1
	s_mov_b32 s99, 0
	global_load_dword v190, v[14:15], off
	v_lshl_add_u64 v[14:15], v[14:15], 0, s[98:99]
	global_load_dword v191, v[14:15], off
	v_lshl_add_u64 v[14:15], v[14:15], 0, s[98:99]
	global_load_dword v192, v[14:15], off
	v_lshl_add_u64 v[14:15], v[14:15], 0, s[98:99]
	global_load_dword v193, v[14:15], off
	v_lshl_add_u64 v[14:15], v[14:15], 0, s[98:99]
	global_load_dword v194, v[14:15], off
	v_lshl_add_u64 v[14:15], v[14:15], 0, s[98:99]
	global_load_dword v195, v[14:15], off
	v_lshl_add_u64 v[14:15], v[14:15], 0, s[98:99]
	global_load_dword v196, v[14:15], off
	v_lshl_add_u64 v[14:15], v[14:15], 0, s[98:99]
	global_load_dword v197, v[14:15], off
	v_lshl_add_u64 v[14:15], v[14:15], 0, s[98:99]
	global_load_dword v198, v[14:15], off
	v_lshl_add_u64 v[14:15], v[14:15], 0, s[98:99]
	global_load_dword v199, v[14:15], off
	v_lshl_add_u64 v[14:15], v[14:15], 0, s[98:99]
	global_load_dword v200, v[14:15], off
	v_lshl_add_u64 v[14:15], v[14:15], 0, s[98:99]
	global_load_dword v201, v[14:15], off
	v_lshl_add_u64 v[14:15], v[14:15], 0, s[98:99]
	global_load_dword v202, v[14:15], off
	v_lshl_add_u64 v[14:15], v[14:15], 0, s[98:99]
	global_load_dword v203, v[14:15], off
	v_lshl_add_u64 v[14:15], v[14:15], 0, s[98:99]
	global_load_dword v204, v[14:15], off
	v_lshl_add_u64 v[14:15], v[14:15], 0, s[98:99]
	global_load_dword v205, v[14:15], off
	s_waitcnt vmcnt(0)
	ds_write_b32 v12, v190
	ds_write_b32 v12, v191 offset:8
	ds_write_b32 v12, v192 offset:16
	ds_write_b32 v12, v193 offset:24
	ds_write_b32 v12, v194 offset:32
	ds_write_b32 v12, v195 offset:40
	ds_write_b32 v12, v196 offset:48
	ds_write_b32 v12, v197 offset:56
	ds_write_b32 v12, v198 offset:64
	ds_write_b32 v12, v199 offset:72
	ds_write_b32 v12, v200 offset:80
	ds_write_b32 v12, v201 offset:88
	ds_write_b32 v12, v202 offset:96
	ds_write_b32 v12, v203 offset:104
	ds_write_b32 v12, v204 offset:112
	ds_write_b32 v12, v205 offset:120

; __device__ __forceinline__ void phase_convert(PP p, int l, LAS unsigned char* lds, int tid, int lane, int wave) {
;     ...
;         for (int item = blockIdx.x; item < 256; item += gridDim.x) {
;             const int kb = item >> 2, g = item & 3, k0 = kb * 32;
;             for (int i = tid; i < 32 * 256; i += 512) { const int r = i >> 8, cc = i & 255; AtT[cc * 36 + r] = w_in[(size_t)(k0 + r) * INP + g * 256 + cc]; }
;             __syncthreads();
.LBB0_93:
	s_lshl_b32 s6, s31, 3
	s_and_b32 s21, s31, 3
	s_and_b32 s20, s6, 0xffffffe0
	s_and_saveexec_b64 s[22:23], vcc
	s_cbranch_execz .LBB0_101
	s_lshl_b32 s76, s21, 10
	v_lshl_add_u64 v[8:9], v[4:5], 0, s[76:77]
	v_ashrrev_i32_e32 v12, 8, v0
	v_add_u32_e32 v14, s20, v12
	v_mad_i64_i32 v[14:15], s[6:7], v14, s0, v[8:9]
	v_lshl_add_u32 v12, v12, 2, v17
	s_lshl_b32 s98, s0, 1
	s_mov_b32 s99, 0
	global_load_dword v100, v[14:15], off
	v_lshl_add_u64 v[14:15], v[14:15], 0, s[98:99]
	global_load_dword v101, v[14:15], off
	v_lshl_add_u64 v[14:15], v[14:15], 0, s[98:99]
	global_load_dword v102, v[14:15], off
	v_lshl_add_u64 v[14:15], v[14:15], 0, s[98:99]
	global_load_dword v103, v[14:15], off
	v_lshl_add_u64 v[14:15], v[14:15], 0, s[98:99]
	global_load_dword v104, v[14:15], off
	v_lshl_add_u64 v[14:15], v[14:15], 0, s[98:99]
	global_load_dword v105, v[14:15], off
	v_lshl_add_u64 v[14:15], v[14:15], 0, s[98:99]
	global_load_dword v106, v[14:15], off
	v_lshl_add_u64 v[14:15], v[14:15], 0, s[98:99]
	global_load_dword v107, v[14:15], off
	v_lshl_add_u64 v[14:15], v[14:15], 0, s[98:99]
	global_load_dword v108, v[14:15], off
	v_lshl_add_u64 v[14:15], v[14:15], 0, s[98:99]
	global_load_dword v109, v[14:15], off
	v_lshl_add_u64 v[14:15], v[14:15], 0, s[98:99]
	global_load_dword v110, v[14:15], off
	v_lshl_add_u64 v[14:15], v[14:15], 0, s[98:99]
	global_load_dword v111, v[14:15], off
	v_lshl_add_u64 v[14:15], v[14:15], 0, s[98:99]
	global_load_dword v112, v[14:15], off
	v_lshl_add_u64 v[14:15], v[14:15], 0, s[98:99]
	global_load_dword v113, v[14:15], off
	v_lshl_add_u64 v[14:15], v[14:15], 0, s[98:99]
	global_load_dword v114, v[14:15], off
	v_lshl_add_u64 v[14:15], v[14:15], 0, s[98:99]
	global_load_dword v115, v[14:15], off
	s_waitcnt vmcnt(0)
	ds_write_b32 v12, v100
	ds_write_b32 v12, v101 offset:8
	ds_write_b32 v12, v102 offset:16
	ds_write_b32 v12, v103 offset:24
	ds_write_b32 v12, v104 offset:32
	ds_write_b32 v12, v105 offset:40
	ds_write_b32 v12, v106 offset:48
	ds_write_b32 v12, v107 offset:56
	ds_write_b32 v12, v108 offset:64
	ds_write_b32 v12, v109 offset:72
	ds_write_b32 v12, v110 offset:80
	ds_write_b32 v12, v111 offset:88
	ds_write_b32 v12, v112 offset:96
	ds_write_b32 v12, v113 offset:104
	ds_write_b32 v12, v114 offset:112
	ds_write_b32 v12, v115 offset:120
